# grid barrier release flattened: followers poll TOPGEN directly, leaders no longer forward through XGEN
# speedup vs baseline: 1.0091x; 1.0091x over previous
; __device__ __forceinline__ unsigned xb_ld(unsigned* p)              { return __hip_atomic_load(p, __ATOMIC_RELAXED, __HIP_MEMORY_SCOPE_AGENT); }
; __device__ __forceinline__ unsigned xb_add(unsigned* p, unsigned v) { return __hip_atomic_fetch_add(p, v, __ATOMIC_RELAXED, __HIP_MEMORY_SCOPE_AGENT); }
; #define XB_SPIN(cond, bar) do { unsigned _sp = 0; while (cond) { __builtin_amdgcn_s_sleep(1); \
;     if ((++_sp & 255u) == 0u) { if (xb_ld(&(bar)[XB_TMO])) break; if (_sp > XB_SPIN_CAP) { atomicAdd(&(bar)[XB_TMO], 1u); break; } } } } while (0)
; __device__ __forceinline__ void xcd_barrier(const XcdBarrier& b) {
;     ...
;         const unsigned old = xb_add(&bar[XB_XSUB(b.x)], 1u);
;         const unsigned gen = old / nloc;
;         if (old + 1u == (gen + 1u) * nloc) {
;             __builtin_amdgcn_fence(__ATOMIC_RELEASE, "agent");
;             asm volatile("s_waitcnt vmcnt(0)" ::: "memory");
;             const unsigned og = xb_add(&bar[XB_TOP], 1u);
;             const unsigned tg = og / nx;
;             if (og + 1u == (tg + 1u) * nx) xb_add(&bar[XB_TOPGEN], 1u);
;             else XB_SPIN(xb_ld(&bar[XB_TOPGEN]) == tg, bar);
;             __builtin_amdgcn_fence(__ATOMIC_ACQUIRE, "agent");
;             xb_add(&bar[XB_XGEN(b.x)], 1u);
;             asm volatile("s_waitcnt vmcnt(0)" ::: "memory");
;         } else {
;             XB_SPIN(xb_ld(&bar[XB_XGEN(b.x)]) == gen, bar);
.LBB0_1005:
	s_or_b64 exec, exec, s[2:3]
	v_cvt_f32_u32_e32 v4, v2
	s_waitcnt vmcnt(0)
	buffer_inv sc1
	v_readfirstlane_b32 s2, v3
	v_sub_u32_e32 v3, 0, v2
	v_rcp_iflag_f32_e32 v4, v4
	v_add_u32_e32 v5, s2, v1
	v_mul_f32_e32 v4, 0x4f7ffffe, v4
	v_cvt_u32_f32_e32 v4, v4
	v_mul_lo_u32 v1, v3, v4
	v_mul_hi_u32 v1, v4, v1
	v_add_u32_e32 v1, v4, v1
	v_mul_hi_u32 v1, v5, v1
	v_mul_lo_u32 v3, v1, v2
	v_sub_u32_e32 v3, v5, v3
	v_add_u32_e32 v4, 1, v1
	v_cmp_ge_u32_e32 vcc, v3, v2
	s_nop 1
	v_cndmask_b32_e32 v1, v1, v4, vcc
	v_sub_u32_e32 v4, v3, v2
	v_cndmask_b32_e32 v3, v3, v4, vcc
	v_add_u32_e32 v4, 1, v1
	v_cmp_ge_u32_e32 vcc, v3, v2
	v_add_u32_e32 v3, 1, v5
	s_nop 0
	v_cndmask_b32_e32 v1, v1, v4, vcc
	v_mul_lo_u32 v4, v2, v1
	v_add_u32_e32 v2, v4, v2
	v_cmp_ne_u32_e32 vcc, v3, v2
	s_and_saveexec_b64 s[2:3], vcc
	s_xor_b64 s[2:3], exec, s[2:3]
	s_cbranch_execz .LBB0_1019
	v_readlane_b32 s4, v254, 17
	v_readlane_b32 s5, v254, 18
	s_waitcnt lgkmcnt(0)
	s_nop 3
	global_load_dword v0, v17, s[4:5] sc1
	s_waitcnt vmcnt(0)
	v_cmp_eq_u32_e32 vcc, v0, v1
	s_and_saveexec_b64 s[4:5], vcc
	s_cbranch_execz .LBB0_1018
	s_mov_b32 s40, 1
	s_mov_b64 s[18:19], 0
	s_branch .LBB0_1009

; __device__ __forceinline__ unsigned xb_ld(unsigned* p)              { return __hip_atomic_load(p, __ATOMIC_RELAXED, __HIP_MEMORY_SCOPE_AGENT); }
; __device__ __forceinline__ unsigned xb_add(unsigned* p, unsigned v) { return __hip_atomic_fetch_add(p, v, __ATOMIC_RELAXED, __HIP_MEMORY_SCOPE_AGENT); }
; #define XB_SPIN(cond, bar) do { unsigned _sp = 0; while (cond) { __builtin_amdgcn_s_sleep(1); \
;     if ((++_sp & 255u) == 0u) { if (xb_ld(&(bar)[XB_TMO])) break; if (_sp > XB_SPIN_CAP) { atomicAdd(&(bar)[XB_TMO], 1u); break; } } } } while (0)
; __device__ __forceinline__ void xcd_barrier(const XcdBarrier& b) {
;     ...
;             else XB_SPIN(xb_ld(&bar[XB_TOPGEN]) == tg, bar);
;             __builtin_amdgcn_fence(__ATOMIC_ACQUIRE, "agent");
;             xb_add(&bar[XB_XGEN(b.x)], 1u);
;             asm volatile("s_waitcnt vmcnt(0)" ::: "memory");
;         } else {
;             XB_SPIN(xb_ld(&bar[XB_XGEN(b.x)]) == gen, bar);
.LBB0_1011:
	v_readlane_b32 s24, v254, 17
	v_readlane_b32 s25, v254, 18
	s_add_i32 s40, s40, 1
	s_mov_b64 s[26:27], -1
	s_nop 2
	global_load_dword v0, v17, s[24:25] sc1
	s_waitcnt vmcnt(0)
	v_cmp_ne_u32_e32 vcc, v0, v1
	s_orn2_b64 s[24:25], vcc, exec
	s_branch .LBB0_1008

; __device__ __forceinline__ unsigned xb_add(unsigned* p, unsigned v) { return __hip_atomic_fetch_add(p, v, __ATOMIC_RELAXED, __HIP_MEMORY_SCOPE_AGENT); }
; __device__ __forceinline__ void xcd_barrier(const XcdBarrier& b) {
;     ...
;             __builtin_amdgcn_fence(__ATOMIC_ACQUIRE, "agent");
;             xb_add(&bar[XB_XGEN(b.x)], 1u);
;             asm volatile("s_waitcnt vmcnt(0)" ::: "memory");
.LBB0_1037:
	s_or_b64 exec, exec, s[2:3]
	s_mov_b64 s[2:3], exec
	v_mbcnt_lo_u32_b32 v0, s2, 0
	v_mbcnt_hi_u32_b32 v0, s3, v0
	v_cmp_eq_u32_e32 vcc, 0, v0
	s_waitcnt vmcnt(0)
	s_and_saveexec_b64 s[4:5], vcc
	s_cbranch_execz .LBB0_1039
	s_bcnt1_i32_b64 s2, s[2:3]
	v_mov_b32_e32 v0, s2
	v_readlane_b32 s2, v254, 13
	v_readlane_b32 s3, v254, 14
	s_nop 4
.LBB0_1039:
	s_or_b64 exec, exec, s[4:5]
	s_waitcnt vmcnt(0)
